# e47: e44 + P1 item swap (vcu 128..133 triple <-> vcu 160..165 single; extras 832..847 to vcu 176..191)
# baseline (speedup 1.0000x reference)
; #define SUB(i, ...) do { if (PROBE_PH == phk && PROBE_SUB == (i)) { __syncthreads(); tp0 = __builtin_amdgcn_s_memrealtime(); } __VA_ARGS__ if (PROBE_PH == phk && PROBE_SUB == (i)) { asm volatile("s_waitcnt vmcnt(0)" ::: "memory"); __syncthreads(); tp1 = __builtin_amdgcn_s_memrealtime(); } } while (0)
; __global__ void __launch_bounds__(NTHREADS, 2) mk_fwd(Args a) {
;     ...
;         SUB(2, if (vcu < 128) transpose_dispatch((320 + vcu) * 8 + wave, a.in[7], a.in[20], a.in[18], a.in[8], a.ws, scr, lane);
;                else { const int b2 = vcu - 128;
;                    for (int it = 448 + 3 * b2; it < 448 + 3 * b2 + 3; ++it) transpose_dispatch(it * 8 + wave, a.in[7], a.in[20], a.in[18], a.in[8], a.ws, scr, lane);
;                    if (b2 < 16) transpose_dispatch((832 + b2) * 8 + wave, a.in[7], a.in[20], a.in[18], a.in[8], a.ws, scr, lane); } );
.LBB0_184:
	s_cmp_eq_u32 s100, 2
	s_cbranch_scc1 .LBB0_230
	s_mov_b32 s99, 0
	s_mul_i32 s2, s53, 0x2100
	s_mov_b32 s13, 0
	s_add_i32 s28, s2, 0
	s_mov_b64 s[2:3], -1
	s_and_b64 vcc, exec, s[18:19]
	s_cbranch_vccz .LBB0_230
	s_mov_b32 s101, 0
	s_cmpk_gt_i32 s81, 0x85
	s_cbranch_scc1 .Lp1_sw1
	s_mov_b32 s101, 32
	s_branch .Lp1_sw2
.Lp1_sw1:
	s_cmpk_lt_i32 s81, 0xa0
	s_cbranch_scc1 .Lp1_sw2
	s_cmpk_gt_i32 s81, 0xa5
	s_cbranch_scc1 .Lp1_sw2
	s_mov_b32 s101, -32
.Lp1_sw2:
	s_add_i32 s81, s81, s101
	s_add_i32 s20, s20, s101

; #define LAS __attribute__((address_space(3)))
; __device__ __forceinline__ f32x4 ld_nt(const float* p) { return __builtin_nontemporal_load((const f32x4*)p); }
; #define SUB(i, ...) do { if (PROBE_PH == phk && PROBE_SUB == (i)) { __syncthreads(); tp0 = __builtin_amdgcn_s_memrealtime(); } __VA_ARGS__ if (PROBE_PH == phk && PROBE_SUB == (i)) { asm volatile("s_waitcnt vmcnt(0)" ::: "memory"); __syncthreads(); tp1 = __builtin_amdgcn_s_memrealtime(); } } while (0)
; __device__ __forceinline__ void transpose_item(const float* W, int K, int pitch, int ncols, f16* WT, LAS float* scr, int item, int lane) {
;     const int nblk = ncols / 32, kb = item / nblk, nb = item % nblk, k0 = 64 * kb, n0 = 32 * nb;
;     const int kr = lane >> 3, nq = (lane & 7) * 4;
;     f32x4 v[8];
; #pragma unroll
;     for (int i = 0; i < 8; ++i) v[i] = ld_nt(W + (size_t)(k0 + kr + 8 * i) * pitch + n0 + nq);
;     __builtin_amdgcn_sched_barrier(0);
; #pragma unroll
;     for (int i = 0; i < 8; ++i) { LAS float* sp = scr + (kr + 8 * i) * 33 + nq; sp[0] = v[i][0]; sp[1] = v[i][1]; sp[2] = v[i][2]; sp[3] = v[i][3]; }
;     asm volatile("s_waitcnt lgkmcnt(0)" ::: "memory");
;     const int c = lane & 7;
; #pragma unroll
;     for (int j = 0; j < 4; ++j) { const int n = (lane >> 3) + 8 * j; const LAS float* sp = scr + (8 * c) * 33 + n;
;         u32x4 o; o.x = pk_f16(sp[0 * 33], sp[1 * 33]); o.y = pk_f16(sp[2 * 33], sp[3 * 33]); o.z = pk_f16(sp[4 * 33], sp[5 * 33]); o.w = pk_f16(sp[6 * 33], sp[7 * 33]);
;         *(u32x4*)(WT + (size_t)(n0 + n) * K + k0 + 8 * c) = o; }
;     asm volatile("s_waitcnt lgkmcnt(0)" ::: "memory");
; }
; __global__ void __launch_bounds__(NTHREADS, 2) mk_fwd(Args a) {
;     ...
;         SUB(2, if (vcu < 128) transpose_dispatch((320 + vcu) * 8 + wave, a.in[7], a.in[20], a.in[18], a.in[8], a.ws, scr, lane);
;                else { const int b2 = vcu - 128;
;                    for (int it = 448 + 3 * b2; it < 448 + 3 * b2 + 3; ++it) transpose_dispatch(it * 8 + wave, a.in[7], a.in[20], a.in[18], a.in[8], a.ws, scr, lane);
;                    if (b2 < 16) transpose_dispatch((832 + b2) * 8 + wave, a.in[7], a.in[20], a.in[18], a.in[8], a.ws, scr, lane); } );
.LBB0_203:
	s_cmp_eq_u32 s99, 1
	s_cbranch_scc1 .Lp3_tr_ret
	s_sub_i32 s81, s81, s101
	s_sub_i32 s20, s20, s101
	s_cmpk_lt_i32 s81, 0xb0
	s_cbranch_scc1 .LBB0_212
	s_cmpk_gt_i32 s81, 0xbf
	s_cbranch_scc1 .LBB0_212
	s_sub_i32 s6, s6, 0x180
	s_add_i32 s7, s6, 0x1600
	s_cmpk_gt_i32 s7, 0x7f
	s_mov_b64 s[12:13], -1
	s_cbranch_scc0 .LBB0_210
	s_lshl_b32 s8, s7, 5
	s_and_b32 s8, s8, 0x7e0
	s_cmpk_gt_u32 s7, 0x167f
	s_mov_b32 s13, 0
	s_mov_b64 s[14:15], -1
	v_or_b32_e32 v9, s8, v24
	v_or_b32_e32 v8, s8, v25
	v_or_b32_e32 v7, s8, v3
	v_or_b32_e32 v6, s8, v1
	s_cbranch_scc0 .LBB0_207
	s_and_b32 s9, s7, 0x7fffffc0
	s_add_i32 s12, s9, 0xffffe980
	s_lshl_b32 s9, s8, 2
	s_add_u32 s14, s40, s9
	v_or_b32_e32 v22, s12, v24
	s_addc_u32 s15, s41, 0
	v_lshlrev_b32_e32 v48, 2, v4
	v_mov_b32_e32 v49, 0
	v_lshl_add_u64 v[40:41], s[14:15], 0, v[48:49]
	v_or_b32_e32 v48, 8, v22
	v_lshlrev_b64 v[12:13], 13, v[48:49]
	v_or_b32_e32 v48, 16, v22
	v_lshlrev_b64 v[18:19], 13, v[48:49]
	v_or_b32_e32 v48, 24, v22
	v_lshlrev_b64 v[20:21], 13, v[48:49]
	v_or_b32_e32 v48, 32, v22
	v_lshlrev_b64 v[32:33], 13, v[48:49]
	v_or_b32_e32 v48, 40, v22
	v_mov_b32_e32 v23, v49
	v_lshlrev_b64 v[34:35], 13, v[48:49]
	v_or_b32_e32 v48, 48, v22
	v_lshlrev_b64 v[10:11], 13, v[22:23]
	v_lshlrev_b64 v[42:43], 13, v[48:49]
	v_or_b32_e32 v48, 56, v22
	v_lshl_add_u64 v[10:11], v[40:41], 0, v[10:11]
	v_lshl_add_u64 v[14:15], v[40:41], 0, v[12:13]
	v_lshl_add_u64 v[18:19], v[40:41], 0, v[18:19]
	v_lshl_add_u64 v[28:29], v[40:41], 0, v[20:21]
	v_lshl_add_u64 v[32:33], v[40:41], 0, v[32:33]
	v_lshl_add_u64 v[36:37], v[40:41], 0, v[34:35]
	v_lshl_add_u64 v[42:43], v[40:41], 0, v[42:43]
	v_lshlrev_b64 v[22:23], 13, v[48:49]
	global_load_dwordx4 v[10:13], v[10:11], off nt
	s_nop 0
	global_load_dwordx4 v[14:17], v[14:15], off nt
	s_nop 0
	global_load_dwordx4 v[18:21], v[18:19], off nt
	s_nop 0
	global_load_dwordx4 v[28:31], v[28:29], off nt
	s_nop 0
	global_load_dwordx4 v[32:35], v[32:33], off nt
	s_nop 0
	global_load_dwordx4 v[36:39], v[36:37], off nt
	v_lshl_add_u64 v[22:23], v[40:41], 0, v[22:23]
	global_load_dwordx4 v[40:43], v[42:43], off nt
	s_nop 0
	global_load_dwordx4 v[44:47], v[22:23], off nt
	s_waitcnt vmcnt(0)
	ds_write2_b32 v26, v10, v11 offset1:1
	ds_write2_b32 v26, v12, v13 offset0:2 offset1:3
	v_add_u32_e32 v10, 0x420, v26
	ds_write2_b32 v10, v14, v15 offset1:1
	v_add_u32_e32 v10, 0x428, v26
	ds_write2_b32 v10, v16, v17 offset1:1
	v_add_u32_e32 v10, 0x840, v26
	ds_write2_b32 v10, v18, v19 offset1:1
	v_add_u32_e32 v10, 0x848, v26
	ds_write2_b32 v10, v20, v21 offset1:1
	v_add_u32_e32 v10, 0xc60, v26
	ds_write2_b32 v10, v28, v29 offset1:1
	v_add_u32_e32 v10, 0xc68, v26
	ds_write2_b32 v10, v30, v31 offset1:1
	v_add_u32_e32 v10, 0x1080, v26
	ds_write2_b32 v10, v32, v33 offset1:1
	v_add_u32_e32 v10, 0x1088, v26
	ds_write2_b32 v10, v34, v35 offset1:1
	v_add_u32_e32 v10, 0x14a0, v26
	ds_write2_b32 v10, v36, v37 offset1:1
	v_add_u32_e32 v10, 0x14a8, v26
	ds_write2_b32 v10, v38, v39 offset1:1
	v_add_u32_e32 v10, 0x18c0, v26
	ds_write2_b32 v10, v40, v41 offset1:1
	v_add_u32_e32 v10, 0x18c8, v26
	ds_write2_b32 v10, v42, v43 offset1:1
	v_add_u32_e32 v10, 0x1ce0, v26
	ds_write2_b32 v10, v44, v45 offset1:1
	v_add_u32_e32 v10, 0x1ce8, v26
	ds_write2_b32 v10, v46, v47 offset1:1
	s_waitcnt lgkmcnt(0)
	ds_read2_b32 v[14:15], v5 offset0:33 offset1:41
	ds_read2_b32 v[16:17], v5 offset1:8
	ds_read2_b32 v[18:19], v5 offset0:66 offset1:74
	ds_read2_b32 v[20:21], v5 offset0:99 offset1:107
	ds_read2_b32 v[22:23], v5 offset0:132 offset1:140
	ds_read2_b32 v[28:29], v5 offset0:165 offset1:173
	ds_read2_b32 v[30:31], v5 offset0:198 offset1:206
	ds_read2_b32 v[32:33], v5 offset0:231 offset1:239
	s_lshl_b64 s[12:13], s[12:13], 1
	s_add_u32 s10, s10, s12
	s_addc_u32 s11, s11, s13
	v_lshlrev_b32_e32 v48, 1, v2
	v_lshl_add_u64 v[34:35], s[10:11], 0, v[48:49]
	v_lshlrev_b32_e32 v48, 11, v9
	s_waitcnt lgkmcnt(6)
	v_cvt_pk_bf16_f32 v10, v16, v14
	s_waitcnt lgkmcnt(4)
	v_cvt_pk_bf16_f32 v11, v18, v20
	s_waitcnt lgkmcnt(2)
	v_cvt_pk_bf16_f32 v12, v22, v28
	s_waitcnt lgkmcnt(0)
	v_cvt_pk_bf16_f32 v13, v30, v32
	v_lshl_add_u64 v[36:37], v[34:35], 0, v[48:49]
	global_store_dwordx4 v[36:37], v[10:13], off
	v_lshlrev_b32_e32 v48, 11, v8
	s_mov_b64 s[14:15], 0
	v_cvt_pk_bf16_f32 v10, v17, v15
	v_cvt_pk_bf16_f32 v11, v19, v21
	v_cvt_pk_bf16_f32 v12, v23, v29
	v_cvt_pk_bf16_f32 v13, v31, v33
	ds_read2_b32 v[16:17], v5 offset0:49 offset1:57
	ds_read2_b32 v[18:19], v5 offset0:16 offset1:24
	ds_read2_b32 v[20:21], v5 offset0:82 offset1:90
	ds_read2_b32 v[22:23], v5 offset0:115 offset1:123
	ds_read2_b32 v[28:29], v5 offset0:148 offset1:156
	ds_read2_b32 v[30:31], v5 offset0:181 offset1:189
	ds_read2_b32 v[32:33], v5 offset0:214 offset1:222
	ds_read2_b32 v[36:37], v5 offset0:247 offset1:255
	v_lshl_add_u64 v[14:15], v[34:35], 0, v[48:49]
	v_lshlrev_b32_e32 v48, 11, v7
	global_store_dwordx4 v[14:15], v[10:13], off
	v_lshl_add_u64 v[14:15], v[34:35], 0, v[48:49]
	v_lshlrev_b32_e32 v48, 11, v6
	s_waitcnt lgkmcnt(6)
	v_cvt_pk_bf16_f32 v10, v18, v16
	s_waitcnt lgkmcnt(4)
	v_cvt_pk_bf16_f32 v11, v20, v22
	s_waitcnt lgkmcnt(2)
	v_cvt_pk_bf16_f32 v12, v28, v30
	s_waitcnt lgkmcnt(0)
	v_cvt_pk_bf16_f32 v13, v32, v36
	global_store_dwordx4 v[14:15], v[10:13], off
	v_lshl_add_u64 v[14:15], v[34:35], 0, v[48:49]
	s_nop 0
	v_cvt_pk_bf16_f32 v10, v19, v17
	v_cvt_pk_bf16_f32 v11, v21, v23
	v_cvt_pk_bf16_f32 v12, v29, v31
	v_cvt_pk_bf16_f32 v13, v33, v37
	global_store_dwordx4 v[14:15], v[10:13], off
	s_waitcnt lgkmcnt(0)
